# speedup vs baseline: 1.0363x; 1.0085x over previous
.LBB0_171:
	s_andn2_b64 vcc, exec, s[8:9]
	s_cbranch_vccnz .LBB0_173
	s_load_dword s98, s[0:1], 0x0
	s_waitcnt lgkmcnt(0)
	s_cmp_eq_u32 s98, 0x100
	s_cbranch_scc0 .Lnsb_do
	s_cmpk_lt_u32 s2, 0x98
	s_cbranch_scc1 .Lnsb_do
	s_cmpk_lt_u32 s2, 0xd8
	s_cbranch_scc0 .Lnsb_do
	s_cmpk_lt_u32 s3, 0x1598
	s_cbranch_scc0 .LBB0_173
.Lnsb_do:
	s_add_i32 s30, s3, 0xffffec80
	s_lshl_b64 s[8:9], s[30:31], 12
	v_lshl_add_u64 v[18:19], s[8:9], 0, v[2:3]
	v_lshl_add_u64 v[14:15], v[18:19], 2, s[54:55]
	global_load_dwordx4 v[10:13], v[14:15], off
	s_nop 0
	global_load_dwordx4 v[14:17], v[14:15], off offset:16
	s_waitcnt vmcnt(1)
	v_cvt_pk_bf16_f32 v10, v10, v11
	v_cvt_pk_bf16_f32 v11, v12, v13
	s_waitcnt vmcnt(0)
	v_cvt_pk_bf16_f32 v12, v14, v15
	v_cvt_pk_bf16_f32 v13, v16, v17
	v_lshl_add_u64 v[14:15], v[18:19], 1, s[20:21]
	global_store_dwordx4 v[14:15], v[10:13], off

.LBB0_174:
	s_andn2_b64 vcc, exec, s[8:9]
	s_cbranch_vccnz .LBB0_178
	s_lshl_b32 s6, s3, 11
	s_and_b32 s6, s6, 0x3800
	s_add_i32 s6, s3, s6
	s_addk_i32 s6, 0xf480
	s_and_b32 s6, s6, -8
	v_add_u32_e32 v10, s6, v36
	v_ashrrev_i32_e32 v11, 31, v10
	v_lshlrev_b64 v[12:13], 12, v[10:11]
	v_lshl_add_u64 v[24:25], v[8:9], 0, v[12:13]
	global_load_dwordx4 v[12:15], v[24:25], off
	global_load_dwordx4 v[70:73], v[24:25], off offset:1024
	global_load_dwordx4 v[74:77], v[24:25], off offset:2048
	global_load_dwordx4 v[78:81], v[24:25], off offset:3072
	v_lshlrev_b64 v[16:17], 11, v[10:11]
	v_lshl_add_u64 v[50:51], v[6:7], 0, v[16:17]
	v_and_b32_e32 v4, 64, v41
	v_add_u32_e32 v4, 64, v4
	v_readlane_b32 s4, v252, 20
	v_readlane_b32 s5, v252, 21
	s_waitcnt vmcnt(3)
	v_cvt_pk_bf16_f32 v16, v12, v13
	v_cvt_pk_bf16_f32 v17, v14, v15
	global_store_dwordx2 v[50:51], v[16:17], off
	v_pk_mul_f32 v[12:13], v[12:13], v[12:13]
	v_pk_mul_f32 v[14:15], v[14:15], v[14:15]
	v_add_f32_e32 v12, v12, v13
	v_add_f32_e32 v12, v12, v14
	s_waitcnt vmcnt(3)
	v_cvt_pk_bf16_f32 v20, v70, v71
	v_cvt_pk_bf16_f32 v21, v72, v73
	global_store_dwordx2 v[50:51], v[20:21], off offset:512
	s_waitcnt vmcnt(3)
	v_cvt_pk_bf16_f32 v46, v74, v75
	v_cvt_pk_bf16_f32 v47, v76, v77
	global_store_dwordx2 v[50:51], v[46:47], off offset:1024
	v_add_f32_e32 v25, v12, v15
	v_pk_mul_f32 v[12:13], v[70:71], v[70:71]
	v_pk_mul_f32 v[14:15], v[72:73], v[72:73]
	v_add_f32_e32 v12, v12, v13
	v_add_f32_e32 v12, v12, v14
	v_add_f32_e32 v12, v12, v15
	v_add_f32_e32 v82, v25, v12
	v_pk_mul_f32 v[12:13], v[74:75], v[74:75]
	v_pk_mul_f32 v[14:15], v[76:77], v[76:77]
	v_add_f32_e32 v12, v12, v13
	v_add_f32_e32 v12, v12, v14
	v_add_f32_e32 v12, v12, v15
	v_add_f32_e32 v82, v82, v12
	v_xor_b32_e32 v24, 32, v41
	v_cmp_lt_i32_e32 vcc, v24, v4
	s_waitcnt vmcnt(3)
	v_pk_mul_f32 v[12:13], v[78:79], v[78:79]
	v_pk_mul_f32 v[14:15], v[80:81], v[80:81]
	v_add_f32_e32 v12, v12, v13
	v_add_f32_e32 v12, v12, v14
	v_cndmask_b32_e32 v24, v41, v24, vcc
	v_add_f32_e32 v12, v12, v15
	v_lshlrev_b32_e32 v24, 2, v24
	v_add_f32_e32 v12, v82, v12
	ds_bpermute_b32 v13, v24, v12
	v_xor_b32_e32 v14, 16, v41
	v_cmp_lt_i32_e32 vcc, v14, v4
	v_cvt_pk_bf16_f32 v15, v80, v81
	s_waitcnt lgkmcnt(0)
	v_add_f32_e32 v12, v12, v13
	v_cndmask_b32_e32 v14, v41, v14, vcc
	v_lshlrev_b32_e32 v14, 2, v14
	ds_bpermute_b32 v13, v14, v12
	v_xor_b32_e32 v14, 8, v41
	v_cmp_lt_i32_e32 vcc, v14, v4
	s_waitcnt lgkmcnt(0)
	v_add_f32_e32 v12, v12, v13
	v_cndmask_b32_e32 v14, v41, v14, vcc
	v_lshlrev_b32_e32 v14, 2, v14
	ds_bpermute_b32 v13, v14, v12
	v_xor_b32_e32 v14, 4, v41
	v_cmp_lt_i32_e32 vcc, v14, v4
	s_waitcnt lgkmcnt(0)
	v_add_f32_e32 v12, v12, v13
	v_cndmask_b32_e32 v14, v41, v14, vcc
	v_lshlrev_b32_e32 v14, 2, v14
	ds_bpermute_b32 v13, v14, v12
	v_xor_b32_e32 v14, 2, v41
	v_cmp_lt_i32_e32 vcc, v14, v4
	s_waitcnt lgkmcnt(0)
	v_add_f32_e32 v12, v12, v13
	v_cndmask_b32_e32 v14, v41, v14, vcc
	v_lshlrev_b32_e32 v14, 2, v14
	ds_bpermute_b32 v13, v14, v12
	v_xor_b32_e32 v14, 1, v41
	v_cmp_lt_i32_e32 vcc, v14, v4
	s_waitcnt lgkmcnt(0)
	v_add_f32_e32 v4, v12, v13
	v_cndmask_b32_e32 v14, v41, v14, vcc
	v_lshlrev_b32_e32 v12, 2, v14
	ds_bpermute_b32 v12, v12, v4
	v_cvt_pk_bf16_f32 v14, v78, v79
	global_store_dwordx2 v[50:51], v[14:15], off offset:1536
	s_and_saveexec_b64 s[8:9], s[4:5]
	s_cbranch_execz .LBB0_177
	s_waitcnt lgkmcnt(0)
	v_add_f32_e32 v4, v4, v12
	v_lshl_add_u64 v[10:11], v[10:11], 2, s[22:23]
	global_store_dword v[10:11], v4, off

.LBB0_223:
	s_load_dword s98, s[0:1], 0x0
	s_waitcnt lgkmcnt(0)
	s_cmp_eq_u32 s98, 0x100
	s_cbranch_scc0 .Lnsb_done
	s_cmpk_lt_u32 s2, 0x98
	s_cbranch_scc1 .Lnsb_lo
	s_cmpk_lt_u32 s2, 0xd8
	s_cbranch_scc1 .Lnsb_done
	s_sub_u32 s98, s2, 64
	s_branch .Lnsb_go
.Lnsb_lo:
	s_mov_b32 s98, s2
.Lnsb_go:
	s_and_b32 s99, s98, 63
	s_lshr_b32 s30, s98, 6
	s_lshl_b32 s30, s30, 8
	s_add_u32 s30, s30, s99
	s_addk_i32 s30, 0x218
	s_lshl_b64 s[8:9], s[30:31], 12
	v_lshl_add_u64 v[18:19], s[8:9], 0, v[2:3]
	v_lshl_add_u64 v[14:15], v[18:19], 2, s[54:55]
	global_load_dwordx4 v[10:13], v[14:15], off
	global_load_dwordx4 v[84:87], v[14:15], off offset:16
	s_add_u32 s98, s98, 0xc0
	s_and_b32 s99, s98, 63
	s_lshr_b32 s30, s98, 6
	s_lshl_b32 s30, s30, 8
	s_add_u32 s30, s30, s99
	s_addk_i32 s30, 0x218
	s_lshl_b64 s[8:9], s[30:31], 12
	v_lshl_add_u64 v[98:99], s[8:9], 0, v[2:3]
	v_lshl_add_u64 v[88:89], v[98:99], 2, s[54:55]
	global_load_dwordx4 v[90:93], v[88:89], off
	global_load_dwordx4 v[94:97], v[88:89], off offset:16
	s_waitcnt vmcnt(3)
	v_cvt_pk_bf16_f32 v10, v10, v11
	v_cvt_pk_bf16_f32 v11, v12, v13
	s_waitcnt vmcnt(2)
	v_cvt_pk_bf16_f32 v12, v84, v85
	v_cvt_pk_bf16_f32 v13, v86, v87
	v_lshl_add_u64 v[14:15], v[18:19], 1, s[20:21]
	global_store_dwordx4 v[14:15], v[10:13], off
	s_waitcnt vmcnt(2)
	v_cvt_pk_bf16_f32 v90, v90, v91
	v_cvt_pk_bf16_f32 v91, v92, v93
	s_waitcnt vmcnt(1)
	v_cvt_pk_bf16_f32 v92, v94, v95
	v_cvt_pk_bf16_f32 v93, v96, v97
	v_lshl_add_u64 v[88:89], v[98:99], 1, s[20:21]
	global_store_dwordx4 v[88:89], v[90:93], off

.Lat_loaded:
	s_waitcnt vmcnt(0)
	s_barrier
	v_lshl_add_u64 v[18:19], v[38:39], 0, s[0:1]
	global_load_dwordx4 v[28:31], v[16:17], off
	global_load_dwordx4 v[32:35], v[18:19], off
	v_lshrrev_b32_e32 v17, 1, v51
	v_ashrrev_i32_e32 v18, 5, v51
	v_and_b32_e32 v17, 48, v17
	v_and_b32_e32 v18, -4, v18
	v_and_b32_e32 v19, 3, v12
	v_lshlrev_b32_e32 v40, 7, v12
	v_xor_b32_e32 v12, v12, v51
	v_add_u32_e32 v17, v17, v18
	v_lshlrev_b32_e32 v12, 4, v12
	v_or_b32_e32 v18, v17, v19
	v_bitop3_b32 v17, v17, v51, v19 bitop3:0x36
	v_and_or_b32 v45, v12, s41, v40
	v_lshlrev_b32_e32 v12, 7, v18
	v_lshlrev_b32_e32 v17, 4, v17
	v_and_or_b32 v46, v17, s41, v12
	v_bfe_u32 v44, v51, 4, 2
	v_add_u32_e32 v12, 0, v46
	v_add_u32_e32 v18, 0, v45
	v_and_b32_e32 v16, 63, v51
	s_bfe_u32 s0, s26, 0x20008
	v_sub_u32_e32 v2, v54, v2
	v_lshlrev_b64 v[40:41], 10, v[14:15]
	v_lshl_add_u32 v47, v13, 2, 0
	v_add_u32_e32 v48, s8, v48
	v_cmp_eq_u32_e64 s[8:9], 0, v16
	s_lshl_b32 s50, s0, 11
	s_lshl_b32 s0, s0, 5
	s_lshl_b32 s26, s27, 1
	v_subrev_u32_e32 v54, 64, v2
	ds_write_b128 v12, v[4:7]
	ds_write_b128 v18, v[8:11] offset:8192
	v_xor_b32_e32 v5, 1, v44
	v_cmp_gt_u32_e64 s[10:11], v5, v44
	v_xor_b32_e32 v5, 2, v44
	v_cmp_gt_u32_e64 s[4:5], v5, v44
	v_xor_b32_e32 v5, 3, v44
	v_and_b32_e32 v4, 7, v51
	v_cmp_gt_u32_e64 s[6:7], v5, v44
	v_lshlrev_b32_e32 v5, 1, v44
	v_bitop3_b32 v6, v44, v51, 7 bitop3:0x78
	v_lshlrev_b32_e32 v49, 4, v6
	v_bitop3_b32 v6, v44, v4, 4 bitop3:0x36
	v_bitop3_b32 v4, v5, v4, 1 bitop3:0x36
	v_lshlrev_b32_e32 v50, 4, v6
	v_bitop3_b32 v6, v5, v51, 7 bitop3:0x78
	v_lshlrev_b32_e32 v52, 4, v4
	v_mov_b32_e32 v4, v3
	v_mov_b32_e32 v5, v3
	v_mov_b32_e32 v2, v3
	v_mov_b64_e32 v[10:11], v[4:5]
	v_mov_b64_e32 v[14:15], v[4:5]
	v_mov_b64_e32 v[18:19], v[4:5]
	v_lshlrev_b32_e32 v51, 4, v6
	s_lshl_b32 s49, s27, 7
	s_or_b32 s0, s0, s26
	v_mov_b64_e32 v[8:9], v[2:3]
	v_mov_b64_e32 v[12:13], v[2:3]
	v_mov_b64_e32 v[16:17], v[2:3]
	v_mov_b64_e32 v[6:7], v[4:5]
	v_mov_b32_e32 v56, 0
	v_lshl_add_u32 v53, v53, 7, 0
	s_add_i32 s26, s0, -1
	s_lshl_b32 s53, s28, 3
	s_or_b32 s51, s49, 64
	s_add_i32 s52, s49, 0x80
	v_mov_b32_e32 v55, 1.0
	s_mov_b32 s54, 0
	v_mov_b64_e32 v[4:5], v[2:3]
	s_mov_b32 s55, 0
	s_and_b64 vcc, exec, s[12:13]
	s_cbranch_vccnz .Lat_nopf
	s_cmp_eq_u32 s33, 32
	s_cbranch_scc0 .Lat_nopf
	s_add_i32 s56, s47, 1
	s_mul_i32 s56, s56, s33
	s_add_i32 s56, s56, s38
	s_cmpk_lt_i32 s56, 0x100
	s_cbranch_scc0 .Lat_nopf
	s_mov_b32 s55, 1
	s_mov_b32 s56, 0x400000
	s_mov_b32 s57, 0
	v_lshl_add_u64 v[112:113], v[112:113], 0, s[56:57]
	global_load_dwordx4 v[118:121], v[110:111], off offset:256
	global_load_dwordx4 v[122:125], v[112:113], off
	global_load_dwordx4 v[126:129], v[114:115], off offset:256
	global_load_dwordx4 v[130:133], v[116:117], off offset:320
